# split-K of the last partial tile round also in gemm_out (layer 0, third round; idle-workgroup weight transposes re-spread), K split 18/14 k-tiles so the publishing half finishes first
# speedup vs baseline: 1.0124x; 1.0020x over previous
.LBB0_455:
	s_mov_b32 s57, s54
	s_mov_b32 s55, 0
	s_mov_b32 s84, 0
	s_mov_b32 s85, 28
	s_cmpk_lt_i32 s99, 0x6c0
	s_cbranch_scc1 .Lgi_sk_dec
	s_cmpk_lt_i32 s54, 0x600
	s_cbranch_scc1 .Lgi_sk_dec
	s_mov_b32 s85, 14
	s_mov_b32 s55, 1
	s_sub_u32 s48, s54, 0x600
	s_cmpk_lt_i32 s54, 0x660
	s_cbranch_scc1 .Lgi_sk_dec
	s_mov_b32 s55, 2
	s_mov_b32 s85, 10
	s_movk_i32 s84, 0x900
	s_sub_u32 s57, s54, 96
	s_sub_u32 s48, s57, 0x600

.LBB0_1159:
	s_or_b64 exec, exec, s[2:3]
	v_readlane_b32 s0, v254, 56
	v_readlane_b32 s1, v254, 57
	s_xor_b64 s[2:3], s[0:1], -1
	v_readlane_b32 s0, v254, 36
	v_readlane_b32 s1, v254, 37
	s_andn2_b64 vcc, exec, s[0:1]
	s_waitcnt lgkmcnt(0)
	s_barrier
	s_cbranch_vccnz .LBB0_1277
	v_readlane_b32 s0, v254, 56
	v_readlane_b32 s1, v254, 57
	s_and_b64 s[0:1], s[0:1], exec
	s_cselect_b32 s16, 0x44, 64
	s_lshl_b32 s46, s16, 3
	v_readlane_b32 s1, v254, 39
	v_readlane_b32 s9, v254, 0
	s_mul_hi_u32 s1, s46, s1
	v_readlane_b32 s10, v254, 38
	s_cmp_lt_i32 s9, s46
	s_mul_i32 s1, s1, s10
	s_cselect_b64 s[12:13], -1, 0
	v_readlane_b32 s20, v255, 0
	s_sub_i32 s1, s46, s1
	s_lshl_b32 s0, s20, 22
	s_sub_i32 s8, s1, s10
	s_cmp_ge_u32 s1, s10
	s_cselect_b32 s1, s8, s1
	s_sub_i32 s8, s1, s10
	s_cmp_ge_u32 s1, s10
	s_cselect_b32 s1, s8, s1
	v_readlane_b32 s8, v254, 1
	s_cmpk_eq_u32 s8, 0x100
	s_cselect_b32 s8, 32, 0
	s_cmpk_eq_u32 s16, 0x44
	s_cselect_b32 s8, s8, 0
	s_add_u32 s1, s1, s8
	s_add_u32 s46, s46, s8
	v_readlane_b32 s10, v254, 1
	s_sub_i32 s47, s10, s1
	v_readlane_b32 s21, v255, 1
	s_cmp_ge_i32 s9, s1
	s_mov_b32 s8, s20
	s_cselect_b64 s[14:15], -1, 0
	s_sub_i32 s52, s9, s1
	s_mov_b32 s21, s17
	v_writelane_b32 v255, s8, 0
	s_lshl_b32 s53, s47, 1
	s_lshl_b64 s[20:21], s[20:21], 23
	v_writelane_b32 v255, s9, 1
	s_mov_b32 s54, 0
	s_lshl_b32 s55, s0, 1
	v_readlane_b32 s11, v254, 2
	s_branch .LBB0_1163

.LBB0_1165:
	s_or_b64 exec, exec, s[0:1]
	s_cmp_eq_u32 s3, 0
	s_cbranch_scc1 .Lgo_sk_epi
	s_load_dwordx2 s[94:95], s[88:89], 0x168
	s_load_dwordx2 s[98:99], s[88:89], 0x170
	v_lshrrev_b32_e32 v170, 6, v167
	v_and_b32_e32 v171, 63, v167
	v_lshlrev_b32_e32 v170, 15, v170
	v_lshl_add_u32 v170, v171, 4, v170
	s_lshl_b32 s2, s32, 18
	s_lshl_b32 s32, s32, 2
	s_add_u32 s32, s32, 0x180
	v_mov_b32_e32 v171, s32
	v_readfirstlane_b32 s32, v167
	s_waitcnt lgkmcnt(0)
	s_add_u32 s94, s94, s2
	s_addc_u32 s95, s95, 0
	s_cmp_eq_u32 s3, 2
	s_cbranch_scc0 .Lgo_sk_fin
	s_nop 7
	s_nop 7
	global_store_dwordx4 v170, v[0:3], s[94:95] sc0 sc1
	global_store_dwordx4 v170, v[4:7], s[94:95] offset:1024 sc0 sc1
	global_store_dwordx4 v170, v[8:11], s[94:95] offset:2048 sc0 sc1
	global_store_dwordx4 v170, v[12:15], s[94:95] offset:3072 sc0 sc1
	v_add_u32_e32 v170, 0x1000, v170
	global_store_dwordx4 v170, v[16:19], s[94:95] sc0 sc1
	global_store_dwordx4 v170, v[20:23], s[94:95] offset:1024 sc0 sc1
	global_store_dwordx4 v170, v[24:27], s[94:95] offset:2048 sc0 sc1
	global_store_dwordx4 v170, v[28:31], s[94:95] offset:3072 sc0 sc1
	v_add_u32_e32 v170, 0x1000, v170
	global_store_dwordx4 v170, v[32:35], s[94:95] sc0 sc1
	global_store_dwordx4 v170, v[36:39], s[94:95] offset:1024 sc0 sc1
	global_store_dwordx4 v170, v[40:43], s[94:95] offset:2048 sc0 sc1
	global_store_dwordx4 v170, v[44:47], s[94:95] offset:3072 sc0 sc1
	v_add_u32_e32 v170, 0x1000, v170
	global_store_dwordx4 v170, v[48:51], s[94:95] sc0 sc1
	global_store_dwordx4 v170, v[52:55], s[94:95] offset:1024 sc0 sc1
	global_store_dwordx4 v170, v[56:59], s[94:95] offset:2048 sc0 sc1
	global_store_dwordx4 v170, v[60:63], s[94:95] offset:3072 sc0 sc1
	v_add_u32_e32 v170, 0x1000, v170
	global_store_dwordx4 v170, v[64:67], s[94:95] sc0 sc1
	global_store_dwordx4 v170, v[68:71], s[94:95] offset:1024 sc0 sc1
	global_store_dwordx4 v170, v[72:75], s[94:95] offset:2048 sc0 sc1
	global_store_dwordx4 v170, v[76:79], s[94:95] offset:3072 sc0 sc1
	v_add_u32_e32 v170, 0x1000, v170
	global_store_dwordx4 v170, v[80:83], s[94:95] sc0 sc1
	global_store_dwordx4 v170, v[84:87], s[94:95] offset:1024 sc0 sc1
	global_store_dwordx4 v170, v[88:91], s[94:95] offset:2048 sc0 sc1
	global_store_dwordx4 v170, v[92:95], s[94:95] offset:3072 sc0 sc1
	v_add_u32_e32 v170, 0x1000, v170
	global_store_dwordx4 v170, v[96:99], s[94:95] sc0 sc1
	global_store_dwordx4 v170, v[100:103], s[94:95] offset:1024 sc0 sc1
	global_store_dwordx4 v170, v[104:107], s[94:95] offset:2048 sc0 sc1
	global_store_dwordx4 v170, v[108:111], s[94:95] offset:3072 sc0 sc1
	v_add_u32_e32 v170, 0x1000, v170
	global_store_dwordx4 v170, v[112:115], s[94:95] sc0 sc1
	global_store_dwordx4 v170, v[116:119], s[94:95] offset:1024 sc0 sc1
	global_store_dwordx4 v170, v[120:123], s[94:95] offset:2048 sc0 sc1
	global_store_dwordx4 v170, v[124:127], s[94:95] offset:3072 sc0 sc1
	v_add_u32_e32 v170, 0x1000, v170
	s_waitcnt vmcnt(0)
	s_barrier
	s_cmp_lt_u32 s32, 64
	s_cbranch_scc0 .Lgo_sk_pend
	s_mov_b64 exec, 1
	v_mov_b32_e32 v172, 1
	global_atomic_add v171, v172, s[98:99]
	s_waitcnt vmcnt(0)
	s_mov_b64 exec, -1
.Lgo_sk_pend:
	s_barrier
	s_branch .LBB0_1172
.Lgo_sk_fin:
	s_cmp_lt_u32 s32, 64
	s_cbranch_scc0 .Lgo_sk_wd
	s_mov_b32 s2, 0
.Lgo_sk_poll:
	global_load_dword v172, v171, s[98:99] sc1
	s_waitcnt vmcnt(0)
	v_readfirstlane_b32 s3, v172
	s_cmp_ge_u32 s3, 1
	s_cbranch_scc1 .Lgo_sk_got
	s_sleep 1
	s_add_u32 s2, s2, 1
	s_cmp_lt_u32 s2, 0x200000
	s_cbranch_scc1 .Lgo_sk_poll

.Lgo_sk_epi:
	v_mov_b32_e32 v129, v167
	v_readlane_b32 s0, v254, 1
	v_ashrrev_i32_e32 v128, 2, v129
	v_and_b32_e32 v130, 15, v129
	v_and_b32_e32 v128, 0xffffffc0, v128
	v_lshrrev_b32_e32 v131, 2, v129
	v_lshrrev_b32_e32 v129, 1, v129
	v_add_u32_e32 v128, s36, v128
	v_and_b32_e32 v129, 0x60, v129
	v_and_or_b32 v128, v131, 12, v128
	v_or3_b32 v130, v130, v129, s34
	v_ashrrev_i32_e32 v131, 31, v130
	v_ashrrev_i32_e32 v129, 31, v128
	v_or_b32_e32 v134, 1, v128
	v_lshl_add_u64 v[130:131], v[130:131], 2, s[26:27]
	v_lshlrev_b64 v[132:133], 13, v[128:129]
	v_ashrrev_i32_e32 v135, 31, v134
	v_lshl_add_u64 v[132:133], v[130:131], 0, v[132:133]
	v_lshlrev_b64 v[134:135], 13, v[134:135]
	global_store_dword v[132:133], v124, off
	v_lshl_add_u64 v[134:135], v[130:131], 0, v[134:135]
	v_or_b32_e32 v124, 2, v128
	v_or_b32_e32 v136, 3, v128
	global_store_dword v[134:135], v125, off
	v_ashrrev_i32_e32 v125, 31, v124
	v_ashrrev_i32_e32 v137, 31, v136
	v_lshlrev_b64 v[124:125], 13, v[124:125]
	v_lshlrev_b64 v[136:137], 13, v[136:137]
	v_lshl_add_u64 v[124:125], v[130:131], 0, v[124:125]
	v_lshl_add_u64 v[136:137], v[130:131], 0, v[136:137]
	global_store_dword v[124:125], v126, off
	global_store_dword v[136:137], v127, off
	global_store_dword v[132:133], v120, off offset:64
	global_store_dword v[134:135], v121, off offset:64
	global_store_dword v[124:125], v122, off offset:64
	global_store_dword v[136:137], v123, off offset:64
	v_or_b32_e32 v120, 16, v128
	v_ashrrev_i32_e32 v121, 31, v120
	v_or_b32_e32 v122, 17, v128
	v_lshlrev_b64 v[120:121], 13, v[120:121]
	v_ashrrev_i32_e32 v123, 31, v122
	v_lshl_add_u64 v[120:121], v[130:131], 0, v[120:121]
	v_lshlrev_b64 v[122:123], 13, v[122:123]
	global_store_dword v[120:121], v116, off
	v_lshl_add_u64 v[122:123], v[130:131], 0, v[122:123]
	v_or_b32_e32 v116, 18, v128
	v_or_b32_e32 v126, 19, v128
	global_store_dword v[122:123], v117, off
	v_ashrrev_i32_e32 v117, 31, v116
	v_ashrrev_i32_e32 v127, 31, v126
	v_lshlrev_b64 v[116:117], 13, v[116:117]
	v_lshlrev_b64 v[126:127], 13, v[126:127]
	v_lshl_add_u64 v[116:117], v[130:131], 0, v[116:117]
	v_lshl_add_u64 v[126:127], v[130:131], 0, v[126:127]
	global_store_dword v[116:117], v118, off
	global_store_dword v[126:127], v119, off
	global_store_dword v[120:121], v112, off offset:64
	global_store_dword v[122:123], v113, off offset:64
	global_store_dword v[116:117], v114, off offset:64
	global_store_dword v[126:127], v115, off offset:64
	v_or_b32_e32 v112, 32, v128
	v_ashrrev_i32_e32 v113, 31, v112
	v_or_b32_e32 v114, 33, v128
	v_lshlrev_b64 v[112:113], 13, v[112:113]
	v_ashrrev_i32_e32 v115, 31, v114
	v_lshl_add_u64 v[112:113], v[130:131], 0, v[112:113]
	v_lshlrev_b64 v[114:115], 13, v[114:115]
	global_store_dword v[112:113], v108, off
	v_lshl_add_u64 v[114:115], v[130:131], 0, v[114:115]
	v_or_b32_e32 v108, 34, v128
	v_or_b32_e32 v118, 35, v128
	global_store_dword v[114:115], v109, off
	v_ashrrev_i32_e32 v109, 31, v108
	v_ashrrev_i32_e32 v119, 31, v118
	v_lshlrev_b64 v[108:109], 13, v[108:109]
	v_lshlrev_b64 v[118:119], 13, v[118:119]
	v_lshl_add_u64 v[108:109], v[130:131], 0, v[108:109]
	v_lshl_add_u64 v[118:119], v[130:131], 0, v[118:119]
	global_store_dword v[108:109], v110, off
	global_store_dword v[118:119], v111, off
	global_store_dword v[112:113], v104, off offset:64
	global_store_dword v[114:115], v105, off offset:64
	global_store_dword v[108:109], v106, off offset:64
	global_store_dword v[118:119], v107, off offset:64
	v_or_b32_e32 v104, 48, v128
	v_ashrrev_i32_e32 v105, 31, v104
	v_or_b32_e32 v106, 49, v128
	v_lshlrev_b64 v[104:105], 13, v[104:105]
	v_ashrrev_i32_e32 v107, 31, v106
	v_lshl_add_u64 v[104:105], v[130:131], 0, v[104:105]
	v_lshlrev_b64 v[106:107], 13, v[106:107]
	global_store_dword v[104:105], v84, off
	v_lshl_add_u64 v[106:107], v[130:131], 0, v[106:107]
	v_or_b32_e32 v84, 50, v128
	v_or_b32_e32 v110, 51, v128
	global_store_dword v[106:107], v85, off
	v_ashrrev_i32_e32 v85, 31, v84
	v_ashrrev_i32_e32 v111, 31, v110
	v_lshlrev_b64 v[84:85], 13, v[84:85]
	v_lshlrev_b64 v[110:111], 13, v[110:111]
	v_lshl_add_u64 v[84:85], v[130:131], 0, v[84:85]
	v_lshl_add_u64 v[110:111], v[130:131], 0, v[110:111]
	global_store_dword v[84:85], v86, off
	global_store_dword v[110:111], v87, off
	global_store_dword v[104:105], v76, off offset:64
	global_store_dword v[106:107], v77, off offset:64
	global_store_dword v[84:85], v78, off offset:64
	global_store_dword v[110:111], v79, off offset:64
	global_store_dword v[132:133], v100, off offset:512
	global_store_dword v[134:135], v101, off offset:512
	global_store_dword v[124:125], v102, off offset:512
	global_store_dword v[136:137], v103, off offset:512
	global_store_dword v[132:133], v96, off offset:576
	global_store_dword v[134:135], v97, off offset:576
	global_store_dword v[124:125], v98, off offset:576
	global_store_dword v[136:137], v99, off offset:576
	global_store_dword v[120:121], v92, off offset:512
	global_store_dword v[122:123], v93, off offset:512
	global_store_dword v[116:117], v94, off offset:512
	global_store_dword v[126:127], v95, off offset:512
	global_store_dword v[120:121], v88, off offset:576
	global_store_dword v[122:123], v89, off offset:576
	global_store_dword v[116:117], v90, off offset:576
	global_store_dword v[126:127], v91, off offset:576
	global_store_dword v[112:113], v80, off offset:512
	global_store_dword v[114:115], v81, off offset:512
	global_store_dword v[108:109], v82, off offset:512
	global_store_dword v[118:119], v83, off offset:512
	global_store_dword v[112:113], v72, off offset:576
	global_store_dword v[114:115], v73, off offset:576
	global_store_dword v[108:109], v74, off offset:576
	global_store_dword v[118:119], v75, off offset:576
	global_store_dword v[104:105], v68, off offset:512
	global_store_dword v[106:107], v69, off offset:512
	global_store_dword v[84:85], v70, off offset:512
	global_store_dword v[110:111], v71, off offset:512
	global_store_dword v[104:105], v64, off offset:576
	global_store_dword v[106:107], v65, off offset:576
	global_store_dword v[84:85], v66, off offset:576
	global_store_dword v[110:111], v67, off offset:576
	v_add_u32_e32 v64, 0x80, v128
	v_ashrrev_i32_e32 v65, 31, v64
	v_add_u32_e32 v66, 0x81, v128
	v_lshlrev_b64 v[64:65], 13, v[64:65]
	v_ashrrev_i32_e32 v67, 31, v66
	v_lshl_add_u64 v[64:65], v[130:131], 0, v[64:65]
	v_lshlrev_b64 v[66:67], 13, v[66:67]
	global_store_dword v[64:65], v60, off
	v_lshl_add_u64 v[66:67], v[130:131], 0, v[66:67]
	v_add_u32_e32 v60, 0x82, v128
	v_add_u32_e32 v68, 0x83, v128
	global_store_dword v[66:67], v61, off
	v_ashrrev_i32_e32 v61, 31, v60
	v_ashrrev_i32_e32 v69, 31, v68
	v_lshlrev_b64 v[60:61], 13, v[60:61]
	v_lshlrev_b64 v[68:69], 13, v[68:69]
	v_lshl_add_u64 v[60:61], v[130:131], 0, v[60:61]
	v_lshl_add_u64 v[68:69], v[130:131], 0, v[68:69]
	global_store_dword v[60:61], v62, off
	global_store_dword v[68:69], v63, off
	global_store_dword v[64:65], v56, off offset:64
	global_store_dword v[66:67], v57, off offset:64
	global_store_dword v[60:61], v58, off offset:64
	global_store_dword v[68:69], v59, off offset:64
	v_add_u32_e32 v56, 0x90, v128
	v_ashrrev_i32_e32 v57, 31, v56
	v_add_u32_e32 v58, 0x91, v128
	v_lshlrev_b64 v[56:57], 13, v[56:57]
	v_ashrrev_i32_e32 v59, 31, v58
	v_lshl_add_u64 v[56:57], v[130:131], 0, v[56:57]
	v_lshlrev_b64 v[58:59], 13, v[58:59]
	global_store_dword v[56:57], v52, off
	v_lshl_add_u64 v[58:59], v[130:131], 0, v[58:59]
	v_add_u32_e32 v52, 0x92, v128
	v_add_u32_e32 v62, 0x93, v128
	global_store_dword v[58:59], v53, off
	v_ashrrev_i32_e32 v53, 31, v52
	v_ashrrev_i32_e32 v63, 31, v62
	v_lshlrev_b64 v[52:53], 13, v[52:53]
	v_lshlrev_b64 v[62:63], 13, v[62:63]
	v_lshl_add_u64 v[52:53], v[130:131], 0, v[52:53]
	v_lshl_add_u64 v[62:63], v[130:131], 0, v[62:63]
	global_store_dword v[52:53], v54, off
	global_store_dword v[62:63], v55, off
	global_store_dword v[56:57], v48, off offset:64
	global_store_dword v[58:59], v49, off offset:64
	global_store_dword v[52:53], v50, off offset:64
	global_store_dword v[62:63], v51, off offset:64
	v_add_u32_e32 v48, 0xa0, v128
	v_ashrrev_i32_e32 v49, 31, v48
	v_add_u32_e32 v50, 0xa1, v128
	v_lshlrev_b64 v[48:49], 13, v[48:49]
	v_ashrrev_i32_e32 v51, 31, v50
	v_lshl_add_u64 v[48:49], v[130:131], 0, v[48:49]
	v_lshlrev_b64 v[50:51], 13, v[50:51]
	global_store_dword v[48:49], v44, off
	v_lshl_add_u64 v[50:51], v[130:131], 0, v[50:51]
	v_add_u32_e32 v44, 0xa2, v128
	v_add_u32_e32 v54, 0xa3, v128
	global_store_dword v[50:51], v45, off
	v_ashrrev_i32_e32 v45, 31, v44
	v_ashrrev_i32_e32 v55, 31, v54
	v_lshlrev_b64 v[44:45], 13, v[44:45]
	v_lshlrev_b64 v[54:55], 13, v[54:55]
	v_lshl_add_u64 v[44:45], v[130:131], 0, v[44:45]
	v_lshl_add_u64 v[54:55], v[130:131], 0, v[54:55]
	global_store_dword v[44:45], v46, off
	global_store_dword v[54:55], v47, off
	global_store_dword v[48:49], v40, off offset:64
	global_store_dword v[50:51], v41, off offset:64
	global_store_dword v[44:45], v42, off offset:64
	global_store_dword v[54:55], v43, off offset:64
	v_add_u32_e32 v40, 0xb0, v128
	v_ashrrev_i32_e32 v41, 31, v40
	v_add_u32_e32 v42, 0xb1, v128
	v_lshlrev_b64 v[40:41], 13, v[40:41]
	v_ashrrev_i32_e32 v43, 31, v42
	v_lshl_add_u64 v[40:41], v[130:131], 0, v[40:41]
	v_lshlrev_b64 v[42:43], 13, v[42:43]
	global_store_dword v[40:41], v36, off
	v_lshl_add_u64 v[42:43], v[130:131], 0, v[42:43]
	v_add_u32_e32 v36, 0xb2, v128
	v_add_u32_e32 v46, 0xb3, v128
	global_store_dword v[42:43], v37, off
	v_ashrrev_i32_e32 v37, 31, v36
	v_ashrrev_i32_e32 v47, 31, v46
	v_lshlrev_b64 v[36:37], 13, v[36:37]
	v_lshlrev_b64 v[46:47], 13, v[46:47]
	s_add_i32 s44, s44, s0
	v_lshl_add_u64 v[36:37], v[130:131], 0, v[36:37]
	v_lshl_add_u64 v[46:47], v[130:131], 0, v[46:47]
	s_cmp_ge_i32 s44, s46
	global_store_dword v[36:37], v38, off
	global_store_dword v[46:47], v39, off
	global_store_dword v[40:41], v28, off offset:64
	global_store_dword v[42:43], v29, off offset:64
	global_store_dword v[36:37], v30, off offset:64
	global_store_dword v[46:47], v31, off offset:64
	global_store_dword v[64:65], v32, off offset:512
	global_store_dword v[66:67], v33, off offset:512
	global_store_dword v[60:61], v34, off offset:512
	global_store_dword v[68:69], v35, off offset:512
	global_store_dword v[64:65], v24, off offset:576
	global_store_dword v[66:67], v25, off offset:576
	global_store_dword v[60:61], v26, off offset:576
	global_store_dword v[68:69], v27, off offset:576
	global_store_dword v[56:57], v20, off offset:512
	global_store_dword v[58:59], v21, off offset:512
	global_store_dword v[52:53], v22, off offset:512
	global_store_dword v[62:63], v23, off offset:512
	global_store_dword v[56:57], v16, off offset:576
	global_store_dword v[58:59], v17, off offset:576
	global_store_dword v[52:53], v18, off offset:576
	global_store_dword v[62:63], v19, off offset:576
	global_store_dword v[48:49], v12, off offset:512
	global_store_dword v[50:51], v13, off offset:512
	global_store_dword v[44:45], v14, off offset:512
	global_store_dword v[54:55], v15, off offset:512
	global_store_dword v[48:49], v8, off offset:576
	global_store_dword v[50:51], v9, off offset:576
	global_store_dword v[44:45], v10, off offset:576
	global_store_dword v[54:55], v11, off offset:576
	global_store_dword v[40:41], v4, off offset:512
	global_store_dword v[42:43], v5, off offset:512
	global_store_dword v[36:37], v6, off offset:512
	global_store_dword v[46:47], v7, off offset:512
	global_store_dword v[40:41], v0, off offset:576
	global_store_dword v[42:43], v1, off offset:576
	global_store_dword v[36:37], v2, off offset:576
	global_store_dword v[46:47], v3, off offset:576
	s_barrier
	v_readlane_b32 s1, v254, 2
	s_cbranch_scc1 .LBB0_1172
.LBB0_1166:
	s_mov_b32 s2, s44
	s_mov_b32 s3, 0
	s_mov_b32 s94, 0
	s_mov_b32 s95, 28
	s_lshl_b32 s32, s16, 3
	s_cmp_eq_u32 s32, s46
	s_cbranch_scc1 .Lgo_sk_dec
	s_cmpk_lt_i32 s44, 0x200
	s_cbranch_scc1 .Lgo_sk_dec
	s_mov_b32 s95, 14
	s_mov_b32 s3, 1
	s_sub_u32 s32, s44, 0x200
	s_cmpk_lt_i32 s44, 0x220
	s_cbranch_scc1 .Lgo_sk_dec
	s_mov_b32 s3, 2
	s_mov_b32 s95, 10
	s_movk_i32 s94, 0x900
	s_sub_u32 s2, s44, 32
	s_sub_u32 s32, s2, 0x200
.Lgo_sk_dec:
	s_ashr_i32 s0, s2, 31
	s_lshr_b32 s0, s0, 29
	s_add_i32 s0, s2, s0
	s_ashr_i32 s1, s0, 3
	s_and_b32 s0, s0, -8
	s_sub_i32 s0, s2, s0
	s_lshr_b32 s34, s0, 31
	s_or_b32 s34, s34, s16
	s_mul_i32 s45, s34, s0
	s_add_i32 s45, s45, s1
	s_ashr_i32 s0, s45, 31
	s_lshr_b32 s0, s0, 26
	s_add_i32 s0, s45, s0
	s_ashr_i32 s48, s0, 6
	s_lshl_b32 s34, s48, 3
	s_sub_i32 s1, s16, s34
	s_min_i32 s35, s1, 8
	s_andn2_b32 s0, s0, 63
	s_sub_i32 s36, s45, s0
	s_sext_i32_i8 s0, s35
	v_cvt_f32_i32_e32 v1, s0
	v_cvt_f32_i32_e32 v0, s36
	s_xor_b32 s1, s36, s0
	s_ashr_i32 s1, s1, 30
	v_rcp_iflag_f32_e32 v2, v1
	s_or_b32 s37, s1, 1
	v_mov_b32_e32 v142, v167
	v_mul_f32_e32 v2, v0, v2
	v_trunc_f32_e32 v2, v2
	v_fma_f32 v0, -v2, v1, v0
	v_cvt_i32_f32_e32 v2, v2
	v_cmp_ge_f32_e64 s[0:1], |v0|, |v1|
	s_and_b64 s[0:1], s[0:1], exec
	s_cselect_b32 s0, s37, 0
	v_readfirstlane_b32 s1, v2
	s_add_i32 s57, s1, s0
	s_sext_i32_i8 s0, s57
	s_mul_i32 s57, s57, s35
	s_sub_i32 s1, s36, s57
	s_sext_i32_i8 s1, s1
	s_add_i32 s34, s34, s1
	s_lshl_b32 s36, s34, 8
	s_ashr_i32 s37, s36, 31
	s_lshl_b32 s34, s0, 8
	s_lshl_b64 s[0:1], s[36:37], 12
	s_add_u32 s38, s24, s0
	v_lshlrev_b32_e32 v12, 4, v142
	v_and_b32_e32 v0, 32, v142
	s_addc_u32 s39, s25, s1
	s_ashr_i32 s35, s34, 31
	v_lshrrev_b32_e32 v1, 1, v142
	v_bitop3_b32 v0, v12, v0, 48 bitop3:0x6c
	s_lshl_b64 s[40:41], s[34:35], 12
	v_lshrrev_b32_e32 v4, 2, v142
	v_and_b32_e32 v10, 32, v1
	v_lshrrev_b32_e32 v11, 1, v0
	v_ashrrev_i32_e32 v14, 3, v142
	v_add_u32_e32 v22, 0x2000, v12
	s_add_u32 s0, s8, s40
	v_or_b32_e32 v0, v11, v10
	v_bfi_b32 v2, 15, v4, v14
	v_ashrrev_i32_e32 v15, 7, v22
	s_addc_u32 s1, s9, s41
	v_lshlrev_b32_e32 v128, 1, v0
	v_add_u32_e32 v128, s94, v128
	v_mov_b32_e32 v129, v165
	v_ashrrev_i32_e32 v3, 31, v2
	v_add_u32_e32 v147, s90, v12
	v_bfi_b32 v4, -16, v15, v4
	v_lshl_add_u64 v[0:1], s[0:1], 0, v[128:129]
	v_lshlrev_b64 v[130:131], 12, v[2:3]
	v_readfirstlane_b32 s0, v147
	v_ashrrev_i32_e32 v5, 31, v4
	v_add_u32_e32 v6, s90, v22
	v_lshl_add_u64 v[2:3], v[0:1], 0, v[130:131]
	s_mov_b32 m0, s0
	v_lshlrev_b64 v[132:133], 12, v[4:5]
	v_readfirstlane_b32 s0, v6
	v_lshl_add_u64 v[16:17], s[38:39], 0, v[128:129]
	v_add_u32_e32 v129, 0, v12
	global_load_lds_dwordx4 v[2:3], off
	v_lshl_add_u64 v[4:5], v[0:1], 0, v[132:133]
	s_mov_b32 m0, s0
	v_readfirstlane_b32 s0, v129
	v_add_u32_e32 v149, 0x2000, v129
	v_readlane_b32 s1, v254, 13
	global_load_lds_dwordx4 v[4:5], off
	v_lshl_add_u64 v[6:7], v[16:17], 0, v[130:131]
	s_mov_b32 m0, s0
	v_readfirstlane_b32 s0, v149
	s_mov_b64 s[84:85], 0x80000
	v_add_u32_e32 v150, s1, v12
	global_load_lds_dwordx4 v[6:7], off
	v_lshl_add_u64 v[8:9], v[16:17], 0, v[132:133]
	s_mov_b32 m0, s0
	v_lshl_add_u64 v[18:19], v[0:1], 0, s[84:85]
	v_readfirstlane_b32 s0, v150
	global_load_lds_dwordx4 v[8:9], off
	v_lshl_add_u64 v[20:21], v[18:19], 0, v[130:131]
	s_mov_b32 m0, s0
	v_add_u32_e32 v151, 0x4000, v129
	global_load_lds_dwordx4 v[20:21], off
	v_add_u32_e32 v20, s1, v22
	v_lshl_add_u64 v[18:19], v[18:19], 0, v[132:133]
	v_readfirstlane_b32 s0, v20
	s_mov_b32 m0, s0
	v_lshl_add_u64 v[16:17], v[16:17], 0, s[84:85]
	v_readfirstlane_b32 s0, v151
	v_add_u32_e32 v152, 0x6000, v129
	global_load_lds_dwordx4 v[18:19], off
	v_lshl_add_u64 v[18:19], v[16:17], 0, v[130:131]
	s_mov_b32 m0, s0
	v_readfirstlane_b32 s0, v152
	global_load_lds_dwordx4 v[18:19], off
	v_lshl_add_u64 v[16:17], v[16:17], 0, v[132:133]
	s_mov_b32 m0, s0
	v_ashrrev_i32_e32 v13, 8, v142
	global_load_lds_dwordx4 v[16:17], off
	v_cmp_eq_u32_e32 vcc, 1, v13
	s_and_saveexec_b64 s[0:1], vcc
	s_cbranch_execz .LBB0_1168
	s_barrier
.LBB0_1168:
	s_or_b64 exec, exec, s[0:1]
	v_readlane_b32 s1, v254, 11
	v_lshl_add_u64 v[2:3], v[2:3], 0, s[96:97]
	v_add_u32_e32 v156, 0x8000, v129
	v_add_u32_e32 v154, s1, v12
	v_add_u32_e32 v155, 0x2000, v154
	v_readfirstlane_b32 s0, v154
	s_mov_b32 m0, s0
	v_readfirstlane_b32 s0, v155
	s_waitcnt vmcnt(4)
	s_barrier
	global_load_lds_dwordx4 v[2:3], off
	v_lshl_add_u64 v[2:3], v[4:5], 0, s[96:97]
	s_mov_b32 m0, s0
	v_readfirstlane_b32 s0, v156
	v_add_u32_e32 v157, 0xa000, v129
	v_readlane_b32 s35, v254, 44
	global_load_lds_dwordx4 v[2:3], off
	v_lshl_add_u64 v[2:3], v[6:7], 0, s[96:97]
	s_mov_b32 m0, s0
	v_readfirstlane_b32 s0, v157
	v_add_u32_e32 v158, s35, v12
	global_load_lds_dwordx4 v[2:3], off
	v_lshl_add_u64 v[2:3], v[8:9], 0, s[96:97]
	s_mov_b32 m0, s0
	v_lshl_add_u64 v[0:1], v[0:1], 0, s[60:61]
	v_readfirstlane_b32 s0, v158
	v_add_u32_e32 v159, 0x2000, v158
	global_load_lds_dwordx4 v[2:3], off
	v_lshl_add_u64 v[2:3], v[0:1], 0, v[130:131]
	s_mov_b32 m0, s0
	v_readfirstlane_b32 s0, v159
	global_load_lds_dwordx4 v[2:3], off
	v_lshl_add_u64 v[0:1], v[0:1], 0, v[132:133]
	s_mov_b32 m0, s0
	v_and_b32_e32 v17, 15, v142
	global_load_lds_dwordx4 v[0:1], off
	v_lshlrev_b32_e32 v1, 2, v142
	v_and_b32_e32 v18, 48, v142
	v_lshlrev_b32_e32 v0, 6, v17
	v_and_b32_e32 v1, 32, v1
	v_bitop3_b32 v0, v0, v1, v18 bitop3:0x36
	v_readlane_b32 s0, v254, 13
	v_lshlrev_b32_e32 v2, 6, v142
	v_bfe_u32 v16, v142, 2, 4
	v_add_u32_e32 v5, s0, v0
	s_movk_i32 s0, 0x3c0
	v_and_b32_e32 v14, -16, v14
	v_and_b32_e32 v15, -16, v15
	v_add_u32_e32 v4, s90, v0
	v_add_u32_e32 v6, s1, v0
	v_add_u32_e32 v7, s35, v0
	v_add_u32_e32 v12, 0, v0
	v_and_or_b32 v0, v2, s0, v18
	v_and_b32_e32 v8, 0x3000, v2
	v_lshlrev_b32_e32 v9, 13, v13
	v_xad_u32 v13, v0, v1, 0
	v_add_u32_e32 v0, v14, v16
	v_add_u32_e32 v2, v15, v16
	v_ashrrev_i32_e32 v1, 31, v0
	s_add_u32 s0, s42, s40
	v_ashrrev_i32_e32 v3, 31, v2
	v_lshlrev_b64 v[0:1], 12, v[0:1]
	s_addc_u32 s1, s43, s41
	v_lshlrev_b64 v[2:3], 12, v[2:3]
	v_lshl_add_u64 v[134:135], s[0:1], 0, v[0:1]
	v_lshl_add_u64 v[136:137], s[0:1], 0, v[2:3]
	s_sub_i32 s1, s45, s57
	s_lshl_b32 s35, s48, 6
	s_sub_i32 s1, s1, s35
	s_sext_i32_i8 s1, s1
	s_lshl_b32 s0, s48, 11
	s_lshl_b32 s1, s1, 8
	s_add_i32 s0, s0, s1
	s_ashr_i32 s1, s0, 31
	s_lshl_b64 s[0:1], s[0:1], 12
	s_add_u32 s0, s24, s0
	s_waitcnt vmcnt(6)
	s_addc_u32 s1, s25, s1
	v_or_b32_e32 v17, 0x800, v9
	v_or_b32_e32 v18, 0x1000, v9
	v_or_b32_e32 v19, 0x1800, v9
	v_lshl_add_u64 v[138:139], s[0:1], 0, v[0:1]
	v_mov_b32_e32 v0, 0
	v_add_lshl_u32 v164, v11, v10, 1
	v_add_u32_e32 v164, s94, v164
	v_lshl_add_u64 v[140:141], s[0:1], 0, v[2:3]
	s_mov_b32 s0, -2
	v_add_u32_e32 v161, v4, v8
	v_add_u32_e32 v146, v12, v9
	v_add_u32_e32 v145, v13, v17
	v_add_u32_e32 v144, v13, v18
	v_add_u32_e32 v143, v13, v19
	v_add_u32_e32 v160, v5, v8
	v_add_u32_e32 v153, v6, v8
	v_add_u32_e32 v148, v7, v8
	v_mov_b32_e32 v1, v0
	v_mov_b32_e32 v2, v0
	v_mov_b32_e32 v3, v0
	v_mov_b32_e32 v4, v0
	v_mov_b32_e32 v5, v0
	v_mov_b32_e32 v6, v0
	v_mov_b32_e32 v7, v0
	v_mov_b32_e32 v8, v0
	v_mov_b32_e32 v9, v0
	v_mov_b32_e32 v10, v0
	v_mov_b32_e32 v11, v0
	v_mov_b32_e32 v12, v0
	v_mov_b32_e32 v13, v0
	v_mov_b32_e32 v14, v0
	v_mov_b32_e32 v15, v0
	v_mov_b32_e32 v16, v0
	v_mov_b32_e32 v17, v0
	v_mov_b32_e32 v18, v0
	v_mov_b32_e32 v19, v0
	v_mov_b32_e32 v20, v0
	v_mov_b32_e32 v21, v0
	v_mov_b32_e32 v22, v0
	v_mov_b32_e32 v23, v0
	v_mov_b32_e32 v24, v0
	v_mov_b32_e32 v25, v0
	v_mov_b32_e32 v26, v0
	v_mov_b32_e32 v27, v0
	v_mov_b32_e32 v28, v0
	v_mov_b32_e32 v29, v0
	v_mov_b32_e32 v30, v0
	v_mov_b32_e32 v31, v0
	v_mov_b32_e32 v32, v0
	v_mov_b32_e32 v33, v0
	v_mov_b32_e32 v34, v0
	v_mov_b32_e32 v35, v0
	v_mov_b32_e32 v36, v0
	v_mov_b32_e32 v37, v0
	v_mov_b32_e32 v38, v0
	v_mov_b32_e32 v39, v0
	v_mov_b32_e32 v40, v0
	v_mov_b32_e32 v41, v0
	v_mov_b32_e32 v42, v0
	v_mov_b32_e32 v43, v0
	v_mov_b32_e32 v44, v0
	v_mov_b32_e32 v45, v0
	v_mov_b32_e32 v46, v0
	v_mov_b32_e32 v47, v0
	v_mov_b32_e32 v48, v0
	v_mov_b32_e32 v49, v0
	v_mov_b32_e32 v50, v0
	v_mov_b32_e32 v51, v0
	v_mov_b32_e32 v52, v0
	v_mov_b32_e32 v53, v0
	v_mov_b32_e32 v54, v0
	v_mov_b32_e32 v55, v0
	v_mov_b32_e32 v56, v0
	v_mov_b32_e32 v57, v0
	v_mov_b32_e32 v58, v0
	v_mov_b32_e32 v59, v0
	v_mov_b32_e32 v60, v0
	v_mov_b32_e32 v61, v0
	v_mov_b32_e32 v62, v0
	v_mov_b32_e32 v63, v0
	v_mov_b32_e32 v64, v0
	v_mov_b32_e32 v65, v0
	v_mov_b32_e32 v66, v0
	v_mov_b32_e32 v67, v0
	v_mov_b32_e32 v68, v0
	v_mov_b32_e32 v69, v0
	v_mov_b32_e32 v70, v0
	v_mov_b32_e32 v71, v0
	v_mov_b32_e32 v72, v0
	v_mov_b32_e32 v73, v0
	v_mov_b32_e32 v74, v0
	v_mov_b32_e32 v75, v0
	v_mov_b32_e32 v76, v0
	v_mov_b32_e32 v77, v0
	v_mov_b32_e32 v78, v0
	v_mov_b32_e32 v79, v0
	v_mov_b32_e32 v80, v0
	v_mov_b32_e32 v81, v0
	v_mov_b32_e32 v82, v0
	v_mov_b32_e32 v83, v0
	v_mov_b32_e32 v84, v0
	v_mov_b32_e32 v85, v0
	v_mov_b32_e32 v86, v0
	v_mov_b32_e32 v87, v0
	v_mov_b32_e32 v88, v0
	v_mov_b32_e32 v89, v0
	v_mov_b32_e32 v90, v0
	v_mov_b32_e32 v91, v0
	v_mov_b32_e32 v92, v0
	v_mov_b32_e32 v93, v0
	v_mov_b32_e32 v94, v0
	v_mov_b32_e32 v95, v0
	v_mov_b32_e32 v96, v0
	v_mov_b32_e32 v97, v0
	v_mov_b32_e32 v98, v0
	v_mov_b32_e32 v99, v0
	v_mov_b32_e32 v100, v0
	v_mov_b32_e32 v101, v0
	v_mov_b32_e32 v102, v0
	v_mov_b32_e32 v103, v0
	v_mov_b32_e32 v104, v0
	v_mov_b32_e32 v105, v0
	v_mov_b32_e32 v106, v0
	v_mov_b32_e32 v107, v0
	v_mov_b32_e32 v108, v0
	v_mov_b32_e32 v109, v0
	v_mov_b32_e32 v110, v0
	v_mov_b32_e32 v111, v0
	v_mov_b32_e32 v112, v0
	v_mov_b32_e32 v113, v0
	v_mov_b32_e32 v114, v0
	v_mov_b32_e32 v115, v0
	v_mov_b32_e32 v116, v0
	v_mov_b32_e32 v117, v0
	v_mov_b32_e32 v118, v0
	v_mov_b32_e32 v119, v0
	v_mov_b32_e32 v120, v0
	v_mov_b32_e32 v121, v0
	v_mov_b32_e32 v122, v0
	v_mov_b32_e32 v123, v0
	v_mov_b32_e32 v124, v0
	v_mov_b32_e32 v125, v0
	v_mov_b32_e32 v126, v0
	v_mov_b32_e32 v127, v0
	s_barrier
.LBB0_1169:
	ds_read_b128 v[168:171], v161
	ds_read_b128 v[172:175], v161 offset:1024
	ds_read_b128 v[176:179], v161 offset:2048
	ds_read_b128 v[194:197], v161 offset:3072
	v_add_u32_e32 v162, 0xc000, v129
	v_lshl_add_u64 v[182:183], v[138:139], 0, v[164:165]
	v_readfirstlane_b32 s1, v162
	v_add_u32_e32 v163, 0xe000, v129
	v_lshl_add_u64 v[230:231], v[182:183], 0, s[60:61]
	s_mov_b32 m0, s1
	v_lshl_add_u64 v[246:247], v[140:141], 0, v[164:165]
	v_readfirstlane_b32 s1, v163
	ds_read_b128 v[198:201], v146
	ds_read_b128 v[202:205], v146 offset:1024
	ds_read_b128 v[206:209], v145
	ds_read_b128 v[210:213], v145 offset:1024
	ds_read_b128 v[214:217], v144
	ds_read_b128 v[218:221], v144 offset:1024
	ds_read_b128 v[222:225], v143
	ds_read_b128 v[226:229], v143 offset:1024
	global_load_lds_dwordx4 v[230:231], off
	v_lshl_add_u64 v[230:231], v[246:247], 0, s[60:61]
	s_mov_b32 m0, s1
	s_nop 0
	global_load_lds_dwordx4 v[230:231], off
	s_waitcnt lgkmcnt(8)
	s_barrier
	s_waitcnt lgkmcnt(0)
	s_setprio 1
	s_waitcnt lgkmcnt(0)
	v_mfma_f32_16x16x32_bf16 v[124:127], v[198:201], v[168:171], v[124:127]
	v_mfma_f32_16x16x32_bf16 v[120:123], v[198:201], v[176:179], v[120:123]
	v_mfma_f32_16x16x32_bf16 v[116:119], v[206:209], v[168:171], v[116:119]
	v_mfma_f32_16x16x32_bf16 v[112:115], v[206:209], v[176:179], v[112:115]
	v_mfma_f32_16x16x32_bf16 v[108:111], v[214:217], v[168:171], v[108:111]
	v_mfma_f32_16x16x32_bf16 v[104:107], v[214:217], v[176:179], v[104:107]
	v_mfma_f32_16x16x32_bf16 v[100:103], v[222:225], v[168:171], v[100:103]
	v_mfma_f32_16x16x32_bf16 v[96:99], v[222:225], v[176:179], v[96:99]
	v_mfma_f32_16x16x32_bf16 v[124:127], v[202:205], v[172:175], v[124:127]
	v_mfma_f32_16x16x32_bf16 v[120:123], v[202:205], v[194:197], v[120:123]
	v_mfma_f32_16x16x32_bf16 v[116:119], v[210:213], v[172:175], v[116:119]
	v_mfma_f32_16x16x32_bf16 v[112:115], v[210:213], v[194:197], v[112:115]
	v_mfma_f32_16x16x32_bf16 v[108:111], v[218:221], v[172:175], v[108:111]
	v_mfma_f32_16x16x32_bf16 v[104:107], v[218:221], v[194:197], v[104:107]
	v_mfma_f32_16x16x32_bf16 v[100:103], v[226:229], v[172:175], v[100:103]
	v_mfma_f32_16x16x32_bf16 v[96:99], v[226:229], v[194:197], v[96:99]
	s_setprio 0
	s_barrier
	v_lshl_add_u64 v[248:249], v[134:135], 0, v[164:165]
	v_readfirstlane_b32 s1, v147
	v_lshl_add_u64 v[250:251], v[248:249], 0, s[62:63]
	s_mov_b32 m0, s1
	v_add_u32_e32 v180, 0x2000, v147
	ds_read_b128 v[230:233], v160
	ds_read_b128 v[234:237], v160 offset:1024
	ds_read_b128 v[238:241], v160 offset:2048
	ds_read_b128 v[242:245], v160 offset:3072
	global_load_lds_dwordx4 v[250:251], off
	v_lshl_add_u64 v[250:251], v[136:137], 0, v[164:165]
	v_readfirstlane_b32 s1, v180
	v_lshl_add_u64 v[252:253], v[250:251], 0, s[62:63]
	s_mov_b32 m0, s1
	s_nop 0
	global_load_lds_dwordx4 v[252:253], off
	s_barrier
	s_waitcnt lgkmcnt(0)
	s_setprio 1
	s_waitcnt lgkmcnt(0)
	v_mfma_f32_16x16x32_bf16 v[92:95], v[198:201], v[230:233], v[92:95]
	v_mfma_f32_16x16x32_bf16 v[88:91], v[198:201], v[238:241], v[88:91]
	v_mfma_f32_16x16x32_bf16 v[84:87], v[206:209], v[230:233], v[84:87]
	v_mfma_f32_16x16x32_bf16 v[80:83], v[206:209], v[238:241], v[80:83]
	v_mfma_f32_16x16x32_bf16 v[76:79], v[214:217], v[230:233], v[76:79]
	v_mfma_f32_16x16x32_bf16 v[72:75], v[214:217], v[238:241], v[72:75]
	v_mfma_f32_16x16x32_bf16 v[68:71], v[222:225], v[230:233], v[68:71]
	v_mfma_f32_16x16x32_bf16 v[64:67], v[222:225], v[238:241], v[64:67]
	v_mfma_f32_16x16x32_bf16 v[92:95], v[202:205], v[234:237], v[92:95]
	v_mfma_f32_16x16x32_bf16 v[88:91], v[202:205], v[242:245], v[88:91]
	v_mfma_f32_16x16x32_bf16 v[84:87], v[210:213], v[234:237], v[84:87]
	v_mfma_f32_16x16x32_bf16 v[80:83], v[210:213], v[242:245], v[80:83]
	v_mfma_f32_16x16x32_bf16 v[76:79], v[218:221], v[234:237], v[76:79]
	v_mfma_f32_16x16x32_bf16 v[72:75], v[218:221], v[242:245], v[72:75]
	v_mfma_f32_16x16x32_bf16 v[68:71], v[226:229], v[234:237], v[68:71]
	v_mfma_f32_16x16x32_bf16 v[64:67], v[226:229], v[242:245], v[64:67]
	s_setprio 0
	v_readfirstlane_b32 s1, v129
	v_lshl_add_u64 v[252:253], v[182:183], 0, s[62:63]
	s_mov_b32 m0, s1
	v_readfirstlane_b32 s1, v149
	s_barrier
	ds_read_b128 v[198:201], v146 offset:16384
	ds_read_b128 v[202:205], v146 offset:17408
	ds_read_b128 v[206:209], v145 offset:16384
	ds_read_b128 v[210:213], v145 offset:17408
	ds_read_b128 v[214:217], v144 offset:16384
	ds_read_b128 v[218:221], v144 offset:17408
	ds_read_b128 v[222:225], v143 offset:16384
	ds_read_b128 v[226:229], v143 offset:17408
	global_load_lds_dwordx4 v[252:253], off
	v_lshl_add_u64 v[252:253], v[246:247], 0, s[62:63]
	s_mov_b32 m0, s1
	s_nop 0
	global_load_lds_dwordx4 v[252:253], off
	s_barrier
	s_waitcnt lgkmcnt(0)
	s_setprio 1
	s_waitcnt lgkmcnt(0)
	v_mfma_f32_16x16x32_bf16 v[60:63], v[198:201], v[168:171], v[60:63]
	v_mfma_f32_16x16x32_bf16 v[56:59], v[198:201], v[176:179], v[56:59]
	v_mfma_f32_16x16x32_bf16 v[52:55], v[206:209], v[168:171], v[52:55]
	v_mfma_f32_16x16x32_bf16 v[48:51], v[206:209], v[176:179], v[48:51]
	v_mfma_f32_16x16x32_bf16 v[44:47], v[214:217], v[168:171], v[44:47]
	v_mfma_f32_16x16x32_bf16 v[40:43], v[214:217], v[176:179], v[40:43]
	v_mfma_f32_16x16x32_bf16 v[36:39], v[222:225], v[168:171], v[36:39]
	v_mfma_f32_16x16x32_bf16 v[32:35], v[222:225], v[176:179], v[32:35]
	v_mfma_f32_16x16x32_bf16 v[60:63], v[202:205], v[172:175], v[60:63]
	v_mfma_f32_16x16x32_bf16 v[56:59], v[202:205], v[194:197], v[56:59]
	v_mfma_f32_16x16x32_bf16 v[52:55], v[210:213], v[172:175], v[52:55]
	v_mfma_f32_16x16x32_bf16 v[48:51], v[210:213], v[194:197], v[48:51]
	v_mfma_f32_16x16x32_bf16 v[44:47], v[218:221], v[172:175], v[44:47]
	v_mfma_f32_16x16x32_bf16 v[40:43], v[218:221], v[194:197], v[40:43]
	v_mfma_f32_16x16x32_bf16 v[36:39], v[226:229], v[172:175], v[36:39]
	v_mfma_f32_16x16x32_bf16 v[32:35], v[226:229], v[194:197], v[32:35]
	s_setprio 0
	s_barrier
	v_readfirstlane_b32 s1, v150
	v_add_u32_e32 v170, 0x2000, v150
	v_lshl_add_u64 v[168:169], v[248:249], 0, s[64:65]
	s_mov_b32 m0, s1
	v_readfirstlane_b32 s1, v170
	global_load_lds_dwordx4 v[168:169], off
	v_lshl_add_u64 v[168:169], v[250:251], 0, s[64:65]
	s_mov_b32 m0, s1
	s_nop 0
	global_load_lds_dwordx4 v[168:169], off
	s_waitcnt vmcnt(6)
	s_barrier
	s_setprio 1
	v_mfma_f32_16x16x32_bf16 v[28:31], v[198:201], v[230:233], v[28:31]
	v_mfma_f32_16x16x32_bf16 v[24:27], v[198:201], v[238:241], v[24:27]
	v_mfma_f32_16x16x32_bf16 v[20:23], v[206:209], v[230:233], v[20:23]
	v_mfma_f32_16x16x32_bf16 v[16:19], v[206:209], v[238:241], v[16:19]
	v_mfma_f32_16x16x32_bf16 v[12:15], v[214:217], v[230:233], v[12:15]
	v_mfma_f32_16x16x32_bf16 v[8:11], v[214:217], v[238:241], v[8:11]
	v_mfma_f32_16x16x32_bf16 v[4:7], v[222:225], v[230:233], v[4:7]
	v_mfma_f32_16x16x32_bf16 v[0:3], v[222:225], v[238:241], v[0:3]
	v_mfma_f32_16x16x32_bf16 v[28:31], v[202:205], v[234:237], v[28:31]
	v_mfma_f32_16x16x32_bf16 v[24:27], v[202:205], v[242:245], v[24:27]
	v_mfma_f32_16x16x32_bf16 v[20:23], v[210:213], v[234:237], v[20:23]
	v_mfma_f32_16x16x32_bf16 v[16:19], v[210:213], v[242:245], v[16:19]
	v_mfma_f32_16x16x32_bf16 v[12:15], v[218:221], v[234:237], v[12:15]
	v_mfma_f32_16x16x32_bf16 v[8:11], v[218:221], v[242:245], v[8:11]
	v_mfma_f32_16x16x32_bf16 v[4:7], v[226:229], v[234:237], v[4:7]
	v_mfma_f32_16x16x32_bf16 v[0:3], v[226:229], v[242:245], v[0:3]
	s_setprio 0
	s_barrier
	ds_read_b128 v[168:171], v153
	ds_read_b128 v[172:175], v153 offset:1024
	ds_read_b128 v[176:179], v153 offset:2048
	ds_read_b128 v[194:197], v153 offset:3072
	v_readfirstlane_b32 s1, v151
	v_lshl_add_u64 v[230:231], v[182:183], 0, s[64:65]
	s_mov_b32 m0, s1
	v_readfirstlane_b32 s1, v152
	ds_read_b128 v[198:201], v146 offset:32768
	ds_read_b128 v[202:205], v146 offset:33792
	ds_read_b128 v[206:209], v145 offset:32768
	ds_read_b128 v[210:213], v145 offset:33792
	ds_read_b128 v[214:217], v144 offset:32768
	ds_read_b128 v[218:221], v144 offset:33792
	ds_read_b128 v[222:225], v143 offset:32768
	ds_read_b128 v[226:229], v143 offset:33792
	global_load_lds_dwordx4 v[230:231], off
	v_lshl_add_u64 v[230:231], v[246:247], 0, s[64:65]
	s_mov_b32 m0, s1
	s_nop 0
	global_load_lds_dwordx4 v[230:231], off
	s_waitcnt lgkmcnt(8)
	s_barrier
	s_waitcnt lgkmcnt(0)
	s_setprio 1
	s_waitcnt lgkmcnt(0)
	v_mfma_f32_16x16x32_bf16 v[124:127], v[198:201], v[168:171], v[124:127]
	v_mfma_f32_16x16x32_bf16 v[120:123], v[198:201], v[176:179], v[120:123]
	v_mfma_f32_16x16x32_bf16 v[116:119], v[206:209], v[168:171], v[116:119]
	v_mfma_f32_16x16x32_bf16 v[112:115], v[206:209], v[176:179], v[112:115]
	v_mfma_f32_16x16x32_bf16 v[108:111], v[214:217], v[168:171], v[108:111]
	v_mfma_f32_16x16x32_bf16 v[104:107], v[214:217], v[176:179], v[104:107]
	v_mfma_f32_16x16x32_bf16 v[100:103], v[222:225], v[168:171], v[100:103]
	v_mfma_f32_16x16x32_bf16 v[96:99], v[222:225], v[176:179], v[96:99]
	v_mfma_f32_16x16x32_bf16 v[124:127], v[202:205], v[172:175], v[124:127]
	v_mfma_f32_16x16x32_bf16 v[120:123], v[202:205], v[194:197], v[120:123]
	v_mfma_f32_16x16x32_bf16 v[116:119], v[210:213], v[172:175], v[116:119]
	v_mfma_f32_16x16x32_bf16 v[112:115], v[210:213], v[194:197], v[112:115]
	v_mfma_f32_16x16x32_bf16 v[108:111], v[218:221], v[172:175], v[108:111]
	v_mfma_f32_16x16x32_bf16 v[104:107], v[218:221], v[194:197], v[104:107]
	v_mfma_f32_16x16x32_bf16 v[100:103], v[226:229], v[172:175], v[100:103]
	v_mfma_f32_16x16x32_bf16 v[96:99], v[226:229], v[194:197], v[96:99]
	s_setprio 0
	s_barrier
	v_readfirstlane_b32 s1, v154
	v_lshl_add_u64 v[252:253], v[248:249], 0, s[6:7]
	s_mov_b32 m0, s1
	v_readfirstlane_b32 s1, v155
	ds_read_b128 v[230:233], v148
	ds_read_b128 v[234:237], v148 offset:1024
	ds_read_b128 v[238:241], v148 offset:2048
	ds_read_b128 v[242:245], v148 offset:3072
	global_load_lds_dwordx4 v[252:253], off
	v_lshl_add_u64 v[252:253], v[250:251], 0, s[6:7]
	s_mov_b32 m0, s1
	s_nop 0
	global_load_lds_dwordx4 v[252:253], off
	s_barrier
	s_waitcnt lgkmcnt(0)
	s_setprio 1
	s_waitcnt lgkmcnt(0)
	v_mfma_f32_16x16x32_bf16 v[92:95], v[198:201], v[230:233], v[92:95]
	v_mfma_f32_16x16x32_bf16 v[88:91], v[198:201], v[238:241], v[88:91]
	v_mfma_f32_16x16x32_bf16 v[84:87], v[206:209], v[230:233], v[84:87]
	v_mfma_f32_16x16x32_bf16 v[80:83], v[206:209], v[238:241], v[80:83]
	v_mfma_f32_16x16x32_bf16 v[76:79], v[214:217], v[230:233], v[76:79]
	v_mfma_f32_16x16x32_bf16 v[72:75], v[214:217], v[238:241], v[72:75]
	v_mfma_f32_16x16x32_bf16 v[68:71], v[222:225], v[230:233], v[68:71]
	v_mfma_f32_16x16x32_bf16 v[64:67], v[222:225], v[238:241], v[64:67]
	v_mfma_f32_16x16x32_bf16 v[92:95], v[202:205], v[234:237], v[92:95]
	v_mfma_f32_16x16x32_bf16 v[88:91], v[202:205], v[242:245], v[88:91]
	v_mfma_f32_16x16x32_bf16 v[84:87], v[210:213], v[234:237], v[84:87]
	v_mfma_f32_16x16x32_bf16 v[80:83], v[210:213], v[242:245], v[80:83]
	v_mfma_f32_16x16x32_bf16 v[76:79], v[218:221], v[234:237], v[76:79]
	v_mfma_f32_16x16x32_bf16 v[72:75], v[218:221], v[242:245], v[72:75]
	v_mfma_f32_16x16x32_bf16 v[68:71], v[226:229], v[234:237], v[68:71]
	v_mfma_f32_16x16x32_bf16 v[64:67], v[226:229], v[242:245], v[64:67]
	s_setprio 0
	v_readfirstlane_b32 s1, v156
	v_lshl_add_u64 v[182:183], v[182:183], 0, s[6:7]
	s_mov_b32 m0, s1
	v_readfirstlane_b32 s1, v157
	s_barrier
	ds_read_b128 v[198:201], v146 offset:49152
	ds_read_b128 v[202:205], v146 offset:50176
	ds_read_b128 v[206:209], v145 offset:49152
	ds_read_b128 v[210:213], v145 offset:50176
	ds_read_b128 v[214:217], v144 offset:49152
	ds_read_b128 v[218:221], v144 offset:50176
	ds_read_b128 v[222:225], v143 offset:49152
	ds_read_b128 v[226:229], v143 offset:50176
	global_load_lds_dwordx4 v[182:183], off
	v_lshl_add_u64 v[182:183], v[246:247], 0, s[6:7]
	s_mov_b32 m0, s1
	s_nop 0
	global_load_lds_dwordx4 v[182:183], off
	s_barrier
	s_waitcnt lgkmcnt(0)
	s_setprio 1
	s_waitcnt lgkmcnt(0)
	v_mfma_f32_16x16x32_bf16 v[60:63], v[198:201], v[168:171], v[60:63]
	v_mfma_f32_16x16x32_bf16 v[56:59], v[198:201], v[176:179], v[56:59]
	v_mfma_f32_16x16x32_bf16 v[52:55], v[206:209], v[168:171], v[52:55]
	v_mfma_f32_16x16x32_bf16 v[48:51], v[206:209], v[176:179], v[48:51]
	v_mfma_f32_16x16x32_bf16 v[44:47], v[214:217], v[168:171], v[44:47]
	v_mfma_f32_16x16x32_bf16 v[40:43], v[214:217], v[176:179], v[40:43]
	v_mfma_f32_16x16x32_bf16 v[36:39], v[222:225], v[168:171], v[36:39]
	v_mfma_f32_16x16x32_bf16 v[32:35], v[222:225], v[176:179], v[32:35]
	v_mfma_f32_16x16x32_bf16 v[60:63], v[202:205], v[172:175], v[60:63]
	v_mfma_f32_16x16x32_bf16 v[56:59], v[202:205], v[194:197], v[56:59]
	v_mfma_f32_16x16x32_bf16 v[52:55], v[210:213], v[172:175], v[52:55]
	v_mfma_f32_16x16x32_bf16 v[48:51], v[210:213], v[194:197], v[48:51]
	v_mfma_f32_16x16x32_bf16 v[44:47], v[218:221], v[172:175], v[44:47]
	v_mfma_f32_16x16x32_bf16 v[40:43], v[218:221], v[194:197], v[40:43]
	v_mfma_f32_16x16x32_bf16 v[36:39], v[226:229], v[172:175], v[36:39]
	v_mfma_f32_16x16x32_bf16 v[32:35], v[226:229], v[194:197], v[32:35]
	s_setprio 0
	s_barrier
	v_readfirstlane_b32 s1, v158
	v_lshl_add_u64 v[168:169], v[248:249], 0, s[92:93]
	s_mov_b32 m0, s1
	v_readfirstlane_b32 s1, v159
	global_load_lds_dwordx4 v[168:169], off
	v_lshl_add_u64 v[168:169], v[250:251], 0, s[92:93]
	s_mov_b32 m0, s1
	s_nop 0
	global_load_lds_dwordx4 v[168:169], off
	s_waitcnt vmcnt(6)
	s_barrier
	s_setprio 1
	v_mfma_f32_16x16x32_bf16 v[28:31], v[198:201], v[230:233], v[28:31]
	v_mfma_f32_16x16x32_bf16 v[24:27], v[198:201], v[238:241], v[24:27]
	v_mfma_f32_16x16x32_bf16 v[20:23], v[206:209], v[230:233], v[20:23]
	v_mfma_f32_16x16x32_bf16 v[16:19], v[206:209], v[238:241], v[16:19]
	v_mfma_f32_16x16x32_bf16 v[12:15], v[214:217], v[230:233], v[12:15]
	v_mfma_f32_16x16x32_bf16 v[8:11], v[214:217], v[238:241], v[8:11]
	v_mfma_f32_16x16x32_bf16 v[4:7], v[222:225], v[230:233], v[4:7]
	v_mfma_f32_16x16x32_bf16 v[0:3], v[222:225], v[238:241], v[0:3]
	v_mfma_f32_16x16x32_bf16 v[28:31], v[202:205], v[234:237], v[28:31]
	v_mfma_f32_16x16x32_bf16 v[24:27], v[202:205], v[242:245], v[24:27]
	v_mfma_f32_16x16x32_bf16 v[20:23], v[210:213], v[234:237], v[20:23]
	v_mfma_f32_16x16x32_bf16 v[16:19], v[210:213], v[242:245], v[16:19]
	v_mfma_f32_16x16x32_bf16 v[12:15], v[218:221], v[234:237], v[12:15]
	v_mfma_f32_16x16x32_bf16 v[8:11], v[218:221], v[242:245], v[8:11]
	v_mfma_f32_16x16x32_bf16 v[4:7], v[226:229], v[234:237], v[4:7]
	v_mfma_f32_16x16x32_bf16 v[0:3], v[226:229], v[242:245], v[0:3]
	s_setprio 0
	s_add_i32 s0, s0, 2
	v_lshl_add_u64 v[134:135], v[134:135], 0, s[62:63]
	v_lshl_add_u64 v[136:137], v[136:137], 0, s[62:63]
	v_lshl_add_u64 v[138:139], v[138:139], 0, s[62:63]
	s_cmp_lt_u32 s0, s95
	v_lshl_add_u64 v[140:141], v[140:141], 0, s[62:63]
	s_barrier
	s_cbranch_scc1 .LBB0_1169
	v_mov_b32_e32 v129, v165
	v_lshl_add_u64 v[128:129], s[38:39], 0, v[128:129]
	s_add_u32 s0, s95, 3
	s_lshl_b32 s0, s0, 7
	s_add_u32 s0, s0, 0x80000
	s_mov_b32 s1, 0
	v_lshl_add_u64 v[128:129], v[128:129], 0, s[0:1]
	v_readfirstlane_b32 s0, v162
	v_lshl_add_u64 v[130:131], v[128:129], 0, v[130:131]
	s_mov_b32 m0, s0
	v_readfirstlane_b32 s0, v163
	ds_read_b128 v[134:137], v161
	ds_read_b128 v[138:141], v161 offset:1024
	ds_read_b128 v[154:157], v161 offset:2048
	ds_read_b128 v[168:171], v161 offset:3072
	ds_read_b128 v[172:175], v146
	ds_read_b128 v[176:179], v146 offset:1024
	ds_read_b128 v[194:197], v145
	ds_read_b128 v[198:201], v145 offset:1024
	ds_read_b128 v[202:205], v144
	ds_read_b128 v[206:209], v144 offset:1024
	ds_read_b128 v[210:213], v143
	ds_read_b128 v[214:217], v143 offset:1024
	global_load_lds_dwordx4 v[130:131], off
	v_lshl_add_u64 v[128:129], v[128:129], 0, v[132:133]
	s_mov_b32 m0, s0
	s_nop 0
	global_load_lds_dwordx4 v[128:129], off
	s_barrier
	s_waitcnt lgkmcnt(0)
	s_setprio 1
	s_waitcnt lgkmcnt(0)
	v_mfma_f32_16x16x32_bf16 v[124:127], v[172:175], v[134:137], v[124:127]
	v_mfma_f32_16x16x32_bf16 v[120:123], v[172:175], v[154:157], v[120:123]
	v_mfma_f32_16x16x32_bf16 v[116:119], v[194:197], v[134:137], v[116:119]
	v_mfma_f32_16x16x32_bf16 v[112:115], v[194:197], v[154:157], v[112:115]
	v_mfma_f32_16x16x32_bf16 v[108:111], v[202:205], v[134:137], v[108:111]
	v_mfma_f32_16x16x32_bf16 v[104:107], v[202:205], v[154:157], v[104:107]
	v_mfma_f32_16x16x32_bf16 v[100:103], v[210:213], v[134:137], v[100:103]
	v_mfma_f32_16x16x32_bf16 v[96:99], v[210:213], v[154:157], v[96:99]
	v_mfma_f32_16x16x32_bf16 v[124:127], v[176:179], v[138:141], v[124:127]
	v_mfma_f32_16x16x32_bf16 v[120:123], v[176:179], v[168:171], v[120:123]
	v_mfma_f32_16x16x32_bf16 v[116:119], v[198:201], v[138:141], v[116:119]
	v_mfma_f32_16x16x32_bf16 v[112:115], v[198:201], v[168:171], v[112:115]
	v_mfma_f32_16x16x32_bf16 v[108:111], v[206:209], v[138:141], v[108:111]
	v_mfma_f32_16x16x32_bf16 v[104:107], v[206:209], v[168:171], v[104:107]
	v_mfma_f32_16x16x32_bf16 v[100:103], v[214:217], v[138:141], v[100:103]
	v_mfma_f32_16x16x32_bf16 v[96:99], v[214:217], v[168:171], v[96:99]
	s_setprio 0
	s_barrier
	ds_read_b128 v[128:131], v160
	ds_read_b128 v[218:221], v160 offset:1024
	ds_read_b128 v[222:225], v160 offset:2048
	ds_read_b128 v[158:161], v160 offset:3072
	s_barrier
	s_waitcnt lgkmcnt(0)
	s_setprio 1
	s_waitcnt lgkmcnt(0)
	v_mfma_f32_16x16x32_bf16 v[92:95], v[172:175], v[128:131], v[92:95]
	v_mfma_f32_16x16x32_bf16 v[88:91], v[172:175], v[222:225], v[88:91]
	v_mfma_f32_16x16x32_bf16 v[80:83], v[194:197], v[222:225], v[80:83]
	v_mfma_f32_16x16x32_bf16 v[72:75], v[202:205], v[222:225], v[72:75]
	v_mfma_f32_16x16x32_bf16 v[68:71], v[210:213], v[128:131], v[68:71]
	v_mfma_f32_16x16x32_bf16 v[64:67], v[210:213], v[222:225], v[64:67]
	v_mfma_f32_16x16x32_bf16 v[92:95], v[176:179], v[218:221], v[92:95]
	v_mfma_f32_16x16x32_bf16 v[88:91], v[176:179], v[158:161], v[88:91]
	v_mfma_f32_16x16x32_bf16 v[84:87], v[194:197], v[128:131], v[84:87]
	v_mfma_f32_16x16x32_bf16 v[80:83], v[198:201], v[158:161], v[80:83]
	v_mfma_f32_16x16x32_bf16 v[76:79], v[202:205], v[128:131], v[76:79]
	v_mfma_f32_16x16x32_bf16 v[72:75], v[206:209], v[158:161], v[72:75]
	v_mfma_f32_16x16x32_bf16 v[68:71], v[214:217], v[218:221], v[68:71]
	v_mfma_f32_16x16x32_bf16 v[64:67], v[214:217], v[158:161], v[64:67]
	v_mfma_f32_16x16x32_bf16 v[172:175], v[198:201], v[218:221], v[84:87]
	v_mfma_f32_16x16x32_bf16 v[176:179], v[206:209], v[218:221], v[76:79]
	s_setprio 0
	s_barrier
	s_nop 0
	ds_read_b128 v[76:79], v146 offset:16384
	ds_read_b128 v[84:87], v146 offset:17408
	ds_read_b128 v[194:197], v145 offset:16384
	ds_read_b128 v[198:201], v145 offset:17408
	ds_read_b128 v[202:205], v144 offset:16384
	ds_read_b128 v[206:209], v144 offset:17408
	ds_read_b128 v[210:213], v143 offset:16384
	ds_read_b128 v[214:217], v143 offset:17408
	s_waitcnt vmcnt(4)
	s_barrier
	s_waitcnt lgkmcnt(0)
	s_setprio 1
	s_waitcnt lgkmcnt(0)
	v_mfma_f32_16x16x32_bf16 v[60:63], v[76:79], v[134:137], v[60:63]
	v_mfma_f32_16x16x32_bf16 v[56:59], v[76:79], v[154:157], v[56:59]
	v_mfma_f32_16x16x32_bf16 v[52:55], v[194:197], v[134:137], v[52:55]
	v_mfma_f32_16x16x32_bf16 v[48:51], v[194:197], v[154:157], v[48:51]
	v_mfma_f32_16x16x32_bf16 v[44:47], v[202:205], v[134:137], v[44:47]
	v_mfma_f32_16x16x32_bf16 v[40:43], v[202:205], v[154:157], v[40:43]
	v_mfma_f32_16x16x32_bf16 v[36:39], v[210:213], v[134:137], v[36:39]
	v_mfma_f32_16x16x32_bf16 v[32:35], v[210:213], v[154:157], v[32:35]
	v_mfma_f32_16x16x32_bf16 v[60:63], v[84:87], v[138:141], v[60:63]
	v_mfma_f32_16x16x32_bf16 v[56:59], v[84:87], v[168:171], v[56:59]
	v_mfma_f32_16x16x32_bf16 v[52:55], v[198:201], v[138:141], v[52:55]
	v_mfma_f32_16x16x32_bf16 v[48:51], v[198:201], v[168:171], v[48:51]
	v_mfma_f32_16x16x32_bf16 v[44:47], v[206:209], v[138:141], v[44:47]
	v_mfma_f32_16x16x32_bf16 v[40:43], v[206:209], v[168:171], v[40:43]
	v_mfma_f32_16x16x32_bf16 v[36:39], v[214:217], v[138:141], v[36:39]
	v_mfma_f32_16x16x32_bf16 v[32:35], v[214:217], v[168:171], v[32:35]
	s_setprio 0
	s_setprio 1
	v_mfma_f32_16x16x32_bf16 v[24:27], v[76:79], v[222:225], v[24:27]
	v_mfma_f32_16x16x32_bf16 v[20:23], v[194:197], v[128:131], v[20:23]
	v_mfma_f32_16x16x32_bf16 v[16:19], v[194:197], v[222:225], v[16:19]
	v_mfma_f32_16x16x32_bf16 v[12:15], v[202:205], v[128:131], v[12:15]
	v_mfma_f32_16x16x32_bf16 v[8:11], v[202:205], v[222:225], v[8:11]
	v_mfma_f32_16x16x32_bf16 v[4:7], v[210:213], v[128:131], v[4:7]
	v_mfma_f32_16x16x32_bf16 v[0:3], v[210:213], v[222:225], v[0:3]
	v_mfma_f32_16x16x32_bf16 v[28:31], v[76:79], v[128:131], v[28:31]
	v_mfma_f32_16x16x32_bf16 v[24:27], v[84:87], v[158:161], v[24:27]
	v_mfma_f32_16x16x32_bf16 v[20:23], v[198:201], v[218:221], v[20:23]
	v_mfma_f32_16x16x32_bf16 v[16:19], v[198:201], v[158:161], v[16:19]
	v_mfma_f32_16x16x32_bf16 v[12:15], v[206:209], v[218:221], v[12:15]
	v_mfma_f32_16x16x32_bf16 v[8:11], v[206:209], v[158:161], v[8:11]
	v_mfma_f32_16x16x32_bf16 v[4:7], v[214:217], v[218:221], v[4:7]
	v_mfma_f32_16x16x32_bf16 v[0:3], v[214:217], v[158:161], v[0:3]
	v_mfma_f32_16x16x32_bf16 v[132:135], v[84:87], v[218:221], v[28:31]
	s_setprio 0
	s_barrier
	s_nop 0
	ds_read_b128 v[28:31], v153
	ds_read_b128 v[128:131], v153 offset:1024
	ds_read_b128 v[136:139], v153 offset:2048
	ds_read_b128 v[150:153], v153 offset:3072
	ds_read_b128 v[154:157], v146 offset:32768
	ds_read_b128 v[158:161], v146 offset:33792
	ds_read_b128 v[168:171], v145 offset:32768
	ds_read_b128 v[194:197], v145 offset:33792
	ds_read_b128 v[198:201], v144 offset:32768
	ds_read_b128 v[202:205], v144 offset:33792
	ds_read_b128 v[206:209], v143 offset:32768
	ds_read_b128 v[210:213], v143 offset:33792
	s_waitcnt vmcnt(2)
	s_barrier
	s_waitcnt lgkmcnt(0)
	s_setprio 1
	s_waitcnt lgkmcnt(0)
	v_mfma_f32_16x16x32_bf16 v[76:79], v[154:157], v[28:31], v[124:127]
	v_mfma_f32_16x16x32_bf16 v[124:127], v[158:161], v[128:131], v[76:79]
	v_mfma_f32_16x16x32_bf16 v[76:79], v[154:157], v[136:139], v[120:123]
	v_mfma_f32_16x16x32_bf16 v[120:123], v[158:161], v[150:153], v[76:79]
	v_mfma_f32_16x16x32_bf16 v[76:79], v[168:171], v[28:31], v[116:119]
	v_mfma_f32_16x16x32_bf16 v[116:119], v[194:197], v[128:131], v[76:79]
	v_mfma_f32_16x16x32_bf16 v[76:79], v[168:171], v[136:139], v[112:115]
	v_mfma_f32_16x16x32_bf16 v[112:115], v[194:197], v[150:153], v[76:79]
	v_mfma_f32_16x16x32_bf16 v[76:79], v[198:201], v[28:31], v[108:111]
	v_mfma_f32_16x16x32_bf16 v[108:111], v[202:205], v[128:131], v[76:79]
	v_mfma_f32_16x16x32_bf16 v[76:79], v[198:201], v[136:139], v[104:107]
	v_mfma_f32_16x16x32_bf16 v[104:107], v[202:205], v[150:153], v[76:79]
	v_mfma_f32_16x16x32_bf16 v[76:79], v[206:209], v[28:31], v[100:103]
	v_mfma_f32_16x16x32_bf16 v[84:87], v[210:213], v[128:131], v[76:79]
	v_mfma_f32_16x16x32_bf16 v[76:79], v[206:209], v[136:139], v[96:99]
	v_mfma_f32_16x16x32_bf16 v[76:79], v[210:213], v[150:153], v[76:79]
	s_setprio 0
	s_barrier
	ds_read_b128 v[214:217], v148
	ds_read_b128 v[218:221], v148 offset:1024
	ds_read_b128 v[222:225], v148 offset:2048
	ds_read_b128 v[226:229], v148 offset:3072
	s_waitcnt vmcnt(0)
	s_barrier
	s_waitcnt lgkmcnt(0)
	s_setprio 1
	s_waitcnt lgkmcnt(0)
	v_mfma_f32_16x16x32_bf16 v[88:91], v[154:157], v[222:225], v[88:91]
	v_mfma_f32_16x16x32_bf16 v[92:95], v[154:157], v[214:217], v[92:95]
	v_mfma_f32_16x16x32_bf16 v[96:99], v[158:161], v[226:229], v[88:91]
	v_mfma_f32_16x16x32_bf16 v[88:91], v[168:171], v[214:217], v[172:175]
	v_mfma_f32_16x16x32_bf16 v[80:83], v[168:171], v[222:225], v[80:83]
	v_mfma_f32_16x16x32_bf16 v[100:103], v[158:161], v[218:221], v[92:95]
	v_mfma_f32_16x16x32_bf16 v[92:95], v[194:197], v[218:221], v[88:91]
	v_mfma_f32_16x16x32_bf16 v[88:91], v[194:197], v[226:229], v[80:83]
	v_mfma_f32_16x16x32_bf16 v[80:83], v[198:201], v[214:217], v[176:179]
	v_mfma_f32_16x16x32_bf16 v[72:75], v[198:201], v[222:225], v[72:75]
	v_mfma_f32_16x16x32_bf16 v[68:71], v[206:209], v[214:217], v[68:71]
	v_mfma_f32_16x16x32_bf16 v[64:67], v[206:209], v[222:225], v[64:67]
	v_mfma_f32_16x16x32_bf16 v[80:83], v[202:205], v[218:221], v[80:83]
	v_mfma_f32_16x16x32_bf16 v[72:75], v[202:205], v[226:229], v[72:75]
	v_mfma_f32_16x16x32_bf16 v[68:71], v[210:213], v[218:221], v[68:71]
	v_mfma_f32_16x16x32_bf16 v[64:67], v[210:213], v[226:229], v[64:67]
	s_setprio 0
	s_barrier
	ds_read_b128 v[154:157], v146 offset:49152
	ds_read_b128 v[146:149], v146 offset:50176
	ds_read_b128 v[158:161], v145 offset:49152
	ds_read_b128 v[168:171], v145 offset:50176
	ds_read_b128 v[172:175], v144 offset:49152
	ds_read_b128 v[176:179], v144 offset:50176
	ds_read_b128 v[194:197], v143 offset:49152
	ds_read_b128 v[198:201], v143 offset:50176
	s_barrier
	s_waitcnt lgkmcnt(0)
	s_setprio 1
	s_waitcnt lgkmcnt(0)
	v_mfma_f32_16x16x32_bf16 v[60:63], v[154:157], v[28:31], v[60:63]
	v_mfma_f32_16x16x32_bf16 v[52:55], v[158:161], v[28:31], v[52:55]
	v_mfma_f32_16x16x32_bf16 v[44:47], v[172:175], v[28:31], v[44:47]
	v_mfma_f32_16x16x32_bf16 v[28:31], v[194:197], v[28:31], v[36:39]
	v_mfma_f32_16x16x32_bf16 v[56:59], v[154:157], v[136:139], v[56:59]
	v_mfma_f32_16x16x32_bf16 v[48:51], v[158:161], v[136:139], v[48:51]
	v_mfma_f32_16x16x32_bf16 v[40:43], v[172:175], v[136:139], v[40:43]
	v_mfma_f32_16x16x32_bf16 v[36:39], v[198:201], v[128:131], v[28:31]
	v_mfma_f32_16x16x32_bf16 v[28:31], v[194:197], v[136:139], v[32:35]
	v_mfma_f32_16x16x32_bf16 v[60:63], v[146:149], v[128:131], v[60:63]
	v_mfma_f32_16x16x32_bf16 v[56:59], v[146:149], v[150:153], v[56:59]
	v_mfma_f32_16x16x32_bf16 v[52:55], v[168:171], v[128:131], v[52:55]
	v_mfma_f32_16x16x32_bf16 v[48:51], v[168:171], v[150:153], v[48:51]
	v_mfma_f32_16x16x32_bf16 v[44:47], v[176:179], v[128:131], v[44:47]
	v_mfma_f32_16x16x32_bf16 v[40:43], v[176:179], v[150:153], v[40:43]
	v_mfma_f32_16x16x32_bf16 v[28:31], v[198:201], v[150:153], v[28:31]
	s_setprio 0
	s_setprio 1
	v_mfma_f32_16x16x32_bf16 v[32:35], v[154:157], v[214:217], v[132:135]
	v_mfma_f32_16x16x32_bf16 v[24:27], v[154:157], v[222:225], v[24:27]
	v_mfma_f32_16x16x32_bf16 v[20:23], v[158:161], v[214:217], v[20:23]
	v_mfma_f32_16x16x32_bf16 v[16:19], v[158:161], v[222:225], v[16:19]
	v_mfma_f32_16x16x32_bf16 v[12:15], v[172:175], v[214:217], v[12:15]
	v_mfma_f32_16x16x32_bf16 v[8:11], v[172:175], v[222:225], v[8:11]
	v_mfma_f32_16x16x32_bf16 v[4:7], v[194:197], v[214:217], v[4:7]
	v_mfma_f32_16x16x32_bf16 v[0:3], v[194:197], v[222:225], v[0:3]
	v_mfma_f32_16x16x32_bf16 v[32:35], v[146:149], v[218:221], v[32:35]
	v_mfma_f32_16x16x32_bf16 v[24:27], v[146:149], v[226:229], v[24:27]
	v_mfma_f32_16x16x32_bf16 v[20:23], v[168:171], v[218:221], v[20:23]
	v_mfma_f32_16x16x32_bf16 v[16:19], v[168:171], v[226:229], v[16:19]
	v_mfma_f32_16x16x32_bf16 v[12:15], v[176:179], v[218:221], v[12:15]
	v_mfma_f32_16x16x32_bf16 v[8:11], v[176:179], v[226:229], v[8:11]
	v_mfma_f32_16x16x32_bf16 v[4:7], v[198:201], v[218:221], v[4:7]
	v_mfma_f32_16x16x32_bf16 v[0:3], v[198:201], v[226:229], v[0:3]
	s_setprio 0
	s_movk_i32 s0, 0x100
	v_cmp_gt_u32_e32 vcc, s0, v142
	s_barrier
	s_and_saveexec_b64 s[0:1], vcc
	s_cbranch_execz .LBB0_1165
	s_barrier
	s_branch .LBB0_1165
